# prep phase kv up-projection GEMM (K=128): the two redundant clamped tile re-loads and the LDS re-store of their data removed, waits on the real tile loads re-counted
# baseline (speedup 1.0000x reference)
; #define G_STORE(S, bf) { *(uint4*)&s->a[bf][srow][skc] = S##a0; *(uint4*)&s->a[bf][srow + 32][skc] = S##a1; \
;     if (MB == 2) { *(uint4*)&s->a[bf][srow + 64][skc] = S##a2; *(uint4*)&s->a[bf][srow + 96][skc] = S##a3; } \
;     *(uint4*)&s->b[bf][srow][skc] = S##b0; *(uint4*)&s->b[bf][srow + 32][skc] = S##b1; *(uint4*)&s->b[bf][srow + 64][skc] = S##b2; *(uint4*)&s->b[bf][srow + 96][skc] = S##b3; }
; template <int MB, bool PF2 = true>
; DI void gemm_main(const u16* __restrict__ A, int lda, const u16* __restrict__ B, int ldb, int K, f32x16 (&acc)[MB][2], GemmLds* s, int tid) {
;     ...
;   for (int kt = 0; kt < KT; kt += 2) {
;     { const int k2 = min((kt + 2) * 64, klast); G_LOAD(q, k2); }
;     __builtin_amdgcn_sched_barrier(0);
;     G_COMPUTE(0);
;     G_STORE(p, 1);
;     __syncthreads();
;     { const int k3 = min((kt + 3) * 64, klast); G_LOAD(p, k3); }
;     __builtin_amdgcn_sched_barrier(0);
;     G_COMPUTE(1);
;     G_STORE(q, 0);
;     __syncthreads();
;   }
.LBB0_749:
	s_add_i32 s14, s14, 2
	ds_read_b128 v[122:125], v199 offset:4608
	ds_read_b128 v[126:129], v200 offset:41472
	ds_read_b128 v[202:205], v199
	ds_read_b128 v[224:227], v199 offset:32
	ds_read_b128 v[228:231], v200 offset:36864
	ds_read_b128 v[232:235], v200 offset:36896
	s_waitcnt lgkmcnt(4)
	v_mfma_f32_32x32x16_bf16 v[2:17], v[122:125], v[126:129], v[2:17]
	s_min_i32 s16, s15, 64
	s_ashr_i32 s17, s16, 31
	s_lshl_b64 s[16:17], s[16:17], 1
	s_add_u32 s18, s6, s16
	s_addc_u32 s19, s7, s17
	s_add_u32 s16, s8, s16
	s_addc_u32 s17, s9, s17
	s_waitcnt lgkmcnt(1)
	v_mfma_f32_32x32x16_bf16 v[50:65], v[202:205], v[228:231], v[50:65]
	v_mfma_f32_32x32x16_bf16 v[34:49], v[202:205], v[126:129], v[34:49]
	v_mfma_f32_32x32x16_bf16 v[18:33], v[122:125], v[228:231], v[18:33]
	ds_read_b128 v[122:125], v199 offset:4640
	ds_read_b128 v[126:129], v200 offset:41504
	s_waitcnt lgkmcnt(2)
	v_mfma_f32_32x32x16_bf16 v[50:65], v[224:227], v[232:235], v[50:65]
	s_waitcnt lgkmcnt(0)
	v_mfma_f32_32x32x16_bf16 v[34:49], v[224:227], v[126:129], v[34:49]
	v_mfma_f32_32x32x16_bf16 v[18:33], v[122:125], v[232:235], v[18:33]
	v_mfma_f32_32x32x16_bf16 v[2:17], v[122:125], v[126:129], v[2:17]
	ds_read_b128 v[122:125], v199 offset:64
	ds_read_b128 v[126:129], v199 offset:4672
	ds_read_b128 v[202:205], v200 offset:36928
	ds_read_b128 v[224:227], v200 offset:41536
	s_waitcnt lgkmcnt(1)
	v_mfma_f32_32x32x16_bf16 v[50:65], v[122:125], v[202:205], v[50:65]
	s_waitcnt lgkmcnt(0)
	v_mfma_f32_32x32x16_bf16 v[34:49], v[122:125], v[224:227], v[34:49]
	v_mfma_f32_32x32x16_bf16 v[18:33], v[126:129], v[202:205], v[18:33]
	v_mfma_f32_32x32x16_bf16 v[2:17], v[126:129], v[224:227], v[2:17]
	ds_read_b128 v[122:125], v199 offset:96
	ds_read_b128 v[126:129], v199 offset:4704
	ds_read_b128 v[202:205], v200 offset:36960
	ds_read_b128 v[224:227], v200 offset:41568
	s_waitcnt vmcnt(7)
	ds_write_b128 v156, v[74:77] offset:18432
	s_waitcnt vmcnt(6)
	ds_write_b128 v156, v[78:81] offset:23040
	s_waitcnt vmcnt(3)
	ds_write_b128 v156, v[82:85] offset:55296
	s_waitcnt vmcnt(2)
	ds_write_b128 v156, v[86:89] offset:59904
	s_waitcnt vmcnt(1)
	ds_write_b128 v156, v[90:93] offset:64512
	s_waitcnt vmcnt(0)
	ds_write_b128 v157, v[94:97] offset:13824
	v_lshl_add_u64 v[74:75], s[18:19], 0, v[132:133]
	v_lshl_add_u64 v[78:79], s[18:19], 0, v[134:135]
	v_lshl_add_u64 v[82:83], s[18:19], 0, v[136:137]
	v_lshl_add_u64 v[84:85], s[18:19], 0, v[138:139]
	v_lshl_add_u64 v[86:87], s[16:17], 0, v[140:141]
	v_lshl_add_u64 v[88:89], s[16:17], 0, v[142:143]
	v_lshl_add_u64 v[90:91], s[16:17], 0, v[144:145]
	v_lshl_add_u64 v[94:95], s[16:17], 0, v[146:147]
	s_waitcnt lgkmcnt(7)
	v_mfma_f32_32x32x16_bf16 v[50:65], v[122:125], v[202:205], v[50:65]
	s_waitcnt lgkmcnt(6)
	v_mfma_f32_32x32x16_bf16 v[34:49], v[122:125], v[224:227], v[34:49]
	v_mfma_f32_32x32x16_bf16 v[18:33], v[126:129], v[202:205], v[18:33]
	v_mfma_f32_32x32x16_bf16 v[2:17], v[126:129], v[224:227], v[2:17]
	ds_write_b128 v156, v[66:69] offset:27648
	ds_write_b128 v156, v[70:73] offset:32256
	s_waitcnt lgkmcnt(0)
	s_barrier
	s_nop 0
	s_nop 0
	s_nop 0
	s_nop 0
	s_nop 0
	s_nop 0
	ds_read_b128 v[202:205], v199 offset:18432
	ds_read_b128 v[224:227], v200 offset:55296
	ds_read_b128 v[228:231], v200 offset:59904
	s_addk_i32 s15, 0x80
	s_cmp_lt_i32 s14, s13
	s_waitcnt lgkmcnt(1)
	v_mfma_f32_32x32x16_bf16 v[50:65], v[202:205], v[224:227], v[50:65]
	s_waitcnt lgkmcnt(0)
	v_mfma_f32_32x32x16_bf16 v[34:49], v[202:205], v[228:231], v[34:49]
	ds_read_b128 v[202:205], v199 offset:23040
	s_waitcnt lgkmcnt(0)
	v_mfma_f32_32x32x16_bf16 v[18:33], v[202:205], v[224:227], v[18:33]
	v_mfma_f32_32x32x16_bf16 v[2:17], v[202:205], v[228:231], v[2:17]
	ds_read_b128 v[202:205], v199 offset:18464
	ds_read_b128 v[224:227], v200 offset:55328
	ds_read_b128 v[228:231], v200 offset:59936
	s_waitcnt lgkmcnt(1)
	v_mfma_f32_32x32x16_bf16 v[50:65], v[202:205], v[224:227], v[50:65]
	s_waitcnt lgkmcnt(0)
	v_mfma_f32_32x32x16_bf16 v[34:49], v[202:205], v[228:231], v[34:49]
	ds_read_b128 v[202:205], v199 offset:23072
	s_waitcnt lgkmcnt(0)
	v_mfma_f32_32x32x16_bf16 v[18:33], v[202:205], v[224:227], v[18:33]
	v_mfma_f32_32x32x16_bf16 v[2:17], v[202:205], v[228:231], v[2:17]
	ds_read_b128 v[202:205], v199 offset:18496
	ds_read_b128 v[224:227], v200 offset:55360
	ds_read_b128 v[228:231], v200 offset:59968
	s_waitcnt lgkmcnt(1)
	v_mfma_f32_32x32x16_bf16 v[50:65], v[202:205], v[224:227], v[50:65]
	s_waitcnt lgkmcnt(0)
	v_mfma_f32_32x32x16_bf16 v[34:49], v[202:205], v[228:231], v[34:49]
	ds_read_b128 v[202:205], v199 offset:23104
	s_waitcnt lgkmcnt(0)
	v_mfma_f32_32x32x16_bf16 v[18:33], v[202:205], v[224:227], v[18:33]
	v_mfma_f32_32x32x16_bf16 v[2:17], v[202:205], v[228:231], v[2:17]
	ds_read_b128 v[202:205], v199 offset:18528
	ds_read_b128 v[224:227], v200 offset:55392
	ds_read_b128 v[228:231], v200 offset:60000
	s_waitcnt lgkmcnt(1)
	v_mfma_f32_32x32x16_bf16 v[50:65], v[202:205], v[224:227], v[50:65]
	s_waitcnt lgkmcnt(0)
	v_mfma_f32_32x32x16_bf16 v[34:49], v[202:205], v[228:231], v[34:49]
	ds_read_b128 v[202:205], v199 offset:23136
	s_waitcnt lgkmcnt(0)
	s_barrier
	v_mfma_f32_32x32x16_bf16 v[18:33], v[202:205], v[224:227], v[18:33]
	v_mfma_f32_32x32x16_bf16 v[2:17], v[202:205], v[228:231], v[2:17]
	s_cbranch_scc1 .LBB0_749
	s_branch .LBB0_751
